# attention queue pop issued one step ahead (atomic in final kv step), counted vmcnt at header
# baseline (speedup 1.0000x reference)
.LBB0_370:
	s_waitcnt lgkmcnt(0)
	s_add_u32 s12, s6, 0xff00
	s_addc_u32 s13, s7, 0
	s_add_u32 s58, s6, 0x8000000
	s_addc_u32 s59, s7, 0
	s_add_u32 s60, s6, 0x9000000
	s_addc_u32 s61, s7, 0
	s_add_u32 s62, s6, 0xa000000
	s_addc_u32 s63, s7, 0
	s_add_u32 s64, s6, 0xb000000
	s_addc_u32 s65, s7, 0
	s_add_u32 s66, s6, 0x80000
	s_addc_u32 s67, s7, 0
	s_add_u32 s68, s6, 0x4000000
	s_addc_u32 s69, s7, 0
	s_add_u32 s70, s6, 0x5000000
	s_addc_u32 s71, s7, 0
	s_add_u32 s72, s6, 0x6000000
	s_addc_u32 s73, s7, 0
	s_add_u32 s74, s6, 0x2000000
	s_mov_b32 s26, 0xffff0000
	s_mov_b32 s17, 0
	v_cmp_eq_u32_e64 s[4:5], 0, v0
	s_addc_u32 s75, s7, 0
	v_mov_b32_e32 v1, 0
	s_add_i32 s76, 0, 0x20178
	s_movk_i32 s77, 0x200
	s_movk_i32 s78, 0x1ff
	s_mov_b64 s[18:19], 0x10000
	s_mov_b64 s[20:21], 0x20000
	s_mov_b64 s[22:23], 0x30000
	s_mov_b64 s[24:25], 0x50000
	s_mov_b32 s27, -1
	s_mov_b32 s79, 0x41000000
	s_mov_b64 s[28:29], 0x40000
	s_mov_b64 s[30:31], 0x80
	s_mov_b64 s[34:35], 0x10080
	v_mov_b32_e32 v236, 0xff800000
	s_mov_b32 s80, 0
	s_mov_b32 s94, 0
	s_branch .LBB0_374

.LBB0_374:
	s_mov_b64 s[8:9], -1
	s_cmp_ge_i32 s80, s57
	s_mov_b64 s[6:7], 0
	s_cbranch_scc0 .LBB0_383
	s_and_saveexec_b64 s[6:7], s[4:5]
	s_cbranch_execz .LBB0_379
	s_cmp_eq_u32 s94, 0
	s_cbranch_scc0 .Lpa_have
	s_mov_b64 s[36:37], exec
	v_mbcnt_lo_u32_b32 v0, s36, 0
	v_mbcnt_hi_u32_b32 v0, s37, v0
	v_cmp_eq_u32_e32 vcc, 0, v0
	s_and_saveexec_b64 s[8:9], vcc
	s_cbranch_execz .LBB0_378
	s_bcnt1_i32_b64 s16, s[36:37]
	v_mov_b32_e32 v2, s16
	global_atomic_add v2, v1, v2, s[12:13] sc0
.LBB0_378:
	s_or_b64 exec, exec, s[8:9]
	s_waitcnt vmcnt(0)
	v_readfirstlane_b32 s8, v2
	v_mov_b32_e32 v2, s76
	s_nop 0
	v_add_u32_e32 v0, s8, v0
	ds_write_b32 v2, v0
	s_branch .LBB0_379
.Lpa_have:
	s_mov_b32 s94, 0
	s_waitcnt vmcnt(8)
	v_mov_b32_e32 v2, s76
	ds_write_b32 v2, v255

.LBB0_474:
	s_add_i32 s95, s80, 1
	s_cmp_ge_i32 s95, s57
	s_cbranch_scc0 .Lpa_skipM
	s_and_saveexec_b64 s[96:97], s[4:5]
	s_cbranch_execz .Lpa_rstM
	v_mov_b32_e32 v254, 1
	global_atomic_add v255, v1, v254, s[12:13] sc0
	s_mov_b32 s94, 1
.Lpa_rstM:
	s_mov_b64 exec, s[96:97]
